# SwiGLU epilogue math of up1/up2 GEMMs regenerated with packed f32 ops (v_pk_mul/v_pk_add), identical arithmetic per element; 128 fewer VALU per wave per unit
# speedup vs baseline: 1.0120x; 1.0020x over previous
; __device__ __forceinline__ unsigned cvt_pk_bf16(float lo, float hi) { unsigned r; asm volatile("v_cvt_pk_bf16_f32 %0, %1, %2" : "=v"(r) : "v"(lo), "v"(hi)); return r; }
; __device__ __forceinline__ float silu_mul(float g, float u) { return g * __builtin_amdgcn_rcpf(1.0f + __builtin_amdgcn_exp2f(-1.4426950408889634f * g)) * u; }
;     __device__ __forceinline__ void operator()(const f32x4 (&acc)[2][2][4][2], const Unit& u, int wr, int wc, int fr, int fq) const {
;         const int row0 = u.pm * BM + wr * 64 + fr, j0 = u.pn * HALF + wc * 32 + 8 * fq;
;         float rs[2][4];
; #pragma unroll
;         for (int ai = 0; ai < 2; ++ai)
; #pragma unroll
;             for (int m = 0; m < 4; ++m) rs[ai][m] = ss[row0 + ai * HALF + m * 16];
;         __builtin_amdgcn_sched_barrier(0);
; #pragma unroll
;         for (int ai = 0; ai < 2; ++ai)
; #pragma unroll
;             for (int m = 0; m < 4; ++m) {
;                 const int row = row0 + ai * HALF + m * 16;
;                 const float r = __builtin_amdgcn_rsqf(rs[ai][m] * (1.0f / DM) + EPSN);
;                 const f32x4 g0 = acc[ai][0][m][0] * r, g1 = acc[ai][0][m][1] * r, u0 = acc[ai][1][m][0] * r, u1 = acc[ai][1][m][1] * r;
;                 u32x4 w;
;                 w.x = cvt_pk_bf16(silu_mul(g0[0], u0[0]), silu_mul(g0[1], u0[1])); w.y = cvt_pk_bf16(silu_mul(g0[2], u0[2]), silu_mul(g0[3], u0[3]));
;                 w.z = cvt_pk_bf16(silu_mul(g1[0], u1[0]), silu_mul(g1[1], u1[1])); w.w = cvt_pk_bf16(silu_mul(g1[2], u1[2]), silu_mul(g1[3], u1[3]));
;                 *(u32x4*)(act + (((size_t)u.pm * (DFF / 64) + (u.pn * 2 + (wc >> 1))) * 256 + (row - u.pm * BM)) * 64 + (wc & 1) * 32 + 8 * fq) = w;
;                 __builtin_amdgcn_sched_barrier(0);
.LBB0_280:
	s_lshl_b32 s27, s38, 8
	v_add_u32_e32 v136, s27, v128
	v_or_b32_e32 v140, 16, v136
	v_ashrrev_i32_e32 v137, 31, v136
	v_ashrrev_i32_e32 v141, 31, v140
	v_lshl_add_u64 v[148:149], v[136:137], 2, s[18:19]
	v_lshl_add_u64 v[138:139], v[140:141], 2, s[18:19]
	global_load_dword v150, v[148:149], off
	global_load_dword v152, v[138:139], off
	v_or_b32_e32 v138, 32, v136
	v_ashrrev_i32_e32 v139, 31, v138
	v_or_b32_e32 v136, 48, v136
	v_lshl_add_u64 v[146:147], v[138:139], 2, s[18:19]
	v_ashrrev_i32_e32 v137, 31, v136
	global_load_dword v153, v[146:147], off
	v_lshl_add_u64 v[146:147], v[136:137], 2, s[18:19]
	global_load_dword v147, v[146:147], off
	s_nop 0
	global_load_dword v146, v[148:149], off offset:512
	global_load_dword v141, v[148:149], off offset:576
	global_load_dword v139, v[148:149], off offset:640
	global_load_dword v137, v[148:149], off offset:704
	s_waitcnt vmcnt(0)
	s_mov_b32 s100, 0xbfb8aa3b
	s_mov_b32 s101, 0xbfb8aa3b
	v_fmamk_f32 v148, v150, 0x3a000000, v145
	v_rsq_f32_e32 v148, v148
	s_lshl_b32 s39, s39, 1
	s_or_b32 s39, s39, s48
	s_mul_hi_i32 s29, s38, 0x56
	v_pk_mul_f32 v[124:125], v[124:125], v[148:149] op_sel_hi:[1,0]
	v_pk_mul_f32 v[150:151], v[114:115], v[148:149] op_sel_hi:[1,0]
	v_pk_mul_f32 v[114:115], v[112:113], v[148:149] op_sel_hi:[1,0]
	v_pk_mul_f32 v[116:117], v[116:117], v[148:149] op_sel_hi:[1,0]
	v_pk_mul_f32 v[126:127], v[126:127], v[148:149] op_sel_hi:[1,0]
	v_pk_mul_f32 v[118:119], v[118:119], v[148:149] op_sel_hi:[1,0]
	v_pk_mul_f32 v[120:121], v[120:121], v[148:149] op_sel_hi:[1,0]
	v_pk_mul_f32 v[122:123], v[122:123], v[148:149] op_sel_hi:[1,0]
	v_pk_mul_f32 v[154:155], v[124:125], s[100:101]
	v_pk_mul_f32 v[156:157], v[126:127], s[100:101]
	v_exp_f32_e32 v154, v154
	v_exp_f32_e32 v155, v155
	v_exp_f32_e32 v156, v156
	v_exp_f32_e32 v157, v157
	v_pk_add_f32 v[154:155], v[154:155], 1.0 op_sel_hi:[1,0]
	v_pk_add_f32 v[156:157], v[156:157], 1.0 op_sel_hi:[1,0]
	v_rcp_f32_e32 v154, v154
	v_rcp_f32_e32 v155, v155
	v_rcp_f32_e32 v156, v156
	v_rcp_f32_e32 v157, v157
	v_pk_mul_f32 v[154:155], v[124:125], v[154:155]
	v_pk_mul_f32 v[156:157], v[126:127], v[156:157]
	v_pk_mul_f32 v[154:155], v[116:117], v[154:155]
	v_pk_mul_f32 v[156:157], v[118:119], v[156:157]
	v_pk_mul_f32 v[158:159], v[120:121], s[100:101]
	v_pk_mul_f32 v[160:161], v[122:123], s[100:101]
	v_exp_f32_e32 v158, v158
	v_exp_f32_e32 v159, v159
	v_exp_f32_e32 v160, v160
	v_exp_f32_e32 v161, v161
	v_pk_add_f32 v[158:159], v[158:159], 1.0 op_sel_hi:[1,0]
	v_pk_add_f32 v[160:161], v[160:161], 1.0 op_sel_hi:[1,0]
	v_rcp_f32_e32 v158, v158
	v_rcp_f32_e32 v159, v159
	v_rcp_f32_e32 v160, v160
	v_rcp_f32_e32 v161, v161
	v_pk_mul_f32 v[158:159], v[120:121], v[158:159]
	v_pk_mul_f32 v[160:161], v[122:123], v[160:161]
	v_pk_mul_f32 v[158:159], v[114:115], v[158:159]
	v_pk_mul_f32 v[160:161], v[150:151], v[160:161]
	v_cvt_pk_bf16_f32 v112, v154, v155
	v_cvt_pk_bf16_f32 v113, v156, v157
	v_cvt_pk_bf16_f32 v114, v158, v159
	v_cvt_pk_bf16_f32 v115, v160, v161
	s_mulk_i32 s38, 0x56
	s_ashr_i32 s40, s39, 31
	s_add_u32 s38, s38, s39
	s_addc_u32 s39, s29, s40
	s_lshl_b64 s[38:39], s[38:39], 15
	s_add_u32 s38, s4, s38
	s_addc_u32 s39, s5, s39
	s_nop 0
	s_nop 0
	v_lshl_add_u64 v[116:117], s[38:39], 0, v[130:131]
	v_lshl_add_u64 v[116:117], v[116:117], 0, s[22:23]
	v_lshl_add_u64 v[116:117], v[116:117], 0, v[200:201]
	global_store_dwordx4 v[116:117], v[112:115], off
	s_nop 1
	v_fmamk_f32 v112, v152, 0x3a000000, v145
	v_rsq_f32_e32 v112, v112
	s_nop 0
	v_pk_mul_f32 v[108:109], v[108:109], v[112:113] op_sel_hi:[1,0]
	v_pk_mul_f32 v[114:115], v[98:99], v[112:113] op_sel_hi:[1,0]
	v_pk_mul_f32 v[98:99], v[96:97], v[112:113] op_sel_hi:[1,0]
	v_pk_mul_f32 v[100:101], v[100:101], v[112:113] op_sel_hi:[1,0]
	v_pk_mul_f32 v[110:111], v[110:111], v[112:113] op_sel_hi:[1,0]
	v_pk_mul_f32 v[102:103], v[102:103], v[112:113] op_sel_hi:[1,0]
	v_pk_mul_f32 v[104:105], v[104:105], v[112:113] op_sel_hi:[1,0]
	v_pk_mul_f32 v[106:107], v[106:107], v[112:113] op_sel_hi:[1,0]
	v_pk_mul_f32 v[154:155], v[108:109], s[100:101]
	v_pk_mul_f32 v[156:157], v[110:111], s[100:101]
	v_exp_f32_e32 v154, v154
	v_exp_f32_e32 v155, v155
	v_exp_f32_e32 v156, v156
	v_exp_f32_e32 v157, v157
	v_pk_add_f32 v[154:155], v[154:155], 1.0 op_sel_hi:[1,0]
	v_pk_add_f32 v[156:157], v[156:157], 1.0 op_sel_hi:[1,0]
	v_rcp_f32_e32 v154, v154
	v_rcp_f32_e32 v155, v155
	v_rcp_f32_e32 v156, v156
	v_rcp_f32_e32 v157, v157
	v_pk_mul_f32 v[154:155], v[108:109], v[154:155]
	v_pk_mul_f32 v[156:157], v[110:111], v[156:157]
	v_pk_mul_f32 v[154:155], v[100:101], v[154:155]
	v_pk_mul_f32 v[156:157], v[102:103], v[156:157]
	v_pk_mul_f32 v[158:159], v[104:105], s[100:101]
	v_pk_mul_f32 v[160:161], v[106:107], s[100:101]
	v_exp_f32_e32 v158, v158
	v_exp_f32_e32 v159, v159
	v_exp_f32_e32 v160, v160
	v_exp_f32_e32 v161, v161
	v_pk_add_f32 v[158:159], v[158:159], 1.0 op_sel_hi:[1,0]
	v_pk_add_f32 v[160:161], v[160:161], 1.0 op_sel_hi:[1,0]
	v_rcp_f32_e32 v158, v158
	v_rcp_f32_e32 v159, v159
	v_rcp_f32_e32 v160, v160
	v_rcp_f32_e32 v161, v161
	v_pk_mul_f32 v[158:159], v[104:105], v[158:159]
	v_pk_mul_f32 v[160:161], v[106:107], v[160:161]
	v_pk_mul_f32 v[158:159], v[98:99], v[158:159]
	v_pk_mul_f32 v[160:161], v[114:115], v[160:161]
	v_cvt_pk_bf16_f32 v96, v154, v155
	v_cvt_pk_bf16_f32 v97, v156, v157
	v_cvt_pk_bf16_f32 v98, v158, v159
	v_cvt_pk_bf16_f32 v99, v160, v161
	s_nop 0
	s_nop 0
	s_nop 0
	s_nop 0
	v_subrev_u32_e32 v100, s27, v140
	v_ashrrev_i32_e32 v101, 31, v100
	v_lshlrev_b64 v[100:101], 7, v[100:101]
	v_lshl_add_u64 v[100:101], s[38:39], 0, v[100:101]
	v_lshl_add_u64 v[100:101], v[100:101], 0, s[22:23]
; __device__ __forceinline__ unsigned cvt_pk_bf16(float lo, float hi) { unsigned r; asm volatile("v_cvt_pk_bf16_f32 %0, %1, %2" : "=v"(r) : "v"(lo), "v"(hi)); return r; }
; __device__ __forceinline__ float silu_mul(float g, float u) { return g * __builtin_amdgcn_rcpf(1.0f + __builtin_amdgcn_exp2f(-1.4426950408889634f * g)) * u; }
;     __device__ __forceinline__ void operator()(const f32x4 (&acc)[2][2][4][2], const Unit& u, int wr, int wc, int fr, int fq) const {
;         const int row0 = u.pm * BM + wr * 64 + fr, j0 = u.pn * HALF + wc * 32 + 8 * fq;
;         float rs[2][4];
; #pragma unroll
;         for (int ai = 0; ai < 2; ++ai)
; #pragma unroll
;             for (int m = 0; m < 4; ++m) rs[ai][m] = ss[row0 + ai * HALF + m * 16];
;         __builtin_amdgcn_sched_barrier(0);
; #pragma unroll
;         for (int ai = 0; ai < 2; ++ai)
; #pragma unroll
;             for (int m = 0; m < 4; ++m) {
;                 const int row = row0 + ai * HALF + m * 16;
;                 const float r = __builtin_amdgcn_rsqf(rs[ai][m] * (1.0f / DM) + EPSN);
;                 const f32x4 g0 = acc[ai][0][m][0] * r, g1 = acc[ai][0][m][1] * r, u0 = acc[ai][1][m][0] * r, u1 = acc[ai][1][m][1] * r;
;                 u32x4 w;
;                 w.x = cvt_pk_bf16(silu_mul(g0[0], u0[0]), silu_mul(g0[1], u0[1])); w.y = cvt_pk_bf16(silu_mul(g0[2], u0[2]), silu_mul(g0[3], u0[3]));
;                 w.z = cvt_pk_bf16(silu_mul(g1[0], u1[0]), silu_mul(g1[1], u1[1])); w.w = cvt_pk_bf16(silu_mul(g1[2], u1[2]), silu_mul(g1[3], u1[3]));
;                 *(u32x4*)(act + (((size_t)u.pm * (DFF / 64) + (u.pn * 2 + (wc >> 1))) * 256 + (row - u.pm * BM)) * 64 + (wc & 1) * 32 + 8 * fq) = w;
;                 __builtin_amdgcn_sched_barrier(0);
	v_lshl_add_u64 v[100:101], v[100:101], 0, v[200:201]
	global_store_dwordx4 v[100:101], v[96:99], off
	s_nop 1
	v_fmamk_f32 v96, v153, 0x3a000000, v145
	v_rsq_f32_e32 v96, v96
	s_nop 0
	v_pk_mul_f32 v[92:93], v[92:93], v[96:97] op_sel_hi:[1,0]
	v_pk_mul_f32 v[98:99], v[82:83], v[96:97] op_sel_hi:[1,0]
	v_pk_mul_f32 v[82:83], v[80:81], v[96:97] op_sel_hi:[1,0]
	v_pk_mul_f32 v[84:85], v[84:85], v[96:97] op_sel_hi:[1,0]
	v_pk_mul_f32 v[94:95], v[94:95], v[96:97] op_sel_hi:[1,0]
	v_pk_mul_f32 v[86:87], v[86:87], v[96:97] op_sel_hi:[1,0]
	v_pk_mul_f32 v[88:89], v[88:89], v[96:97] op_sel_hi:[1,0]
	v_pk_mul_f32 v[90:91], v[90:91], v[96:97] op_sel_hi:[1,0]
	v_pk_mul_f32 v[154:155], v[92:93], s[100:101]
	v_pk_mul_f32 v[156:157], v[94:95], s[100:101]
	v_exp_f32_e32 v154, v154
	v_exp_f32_e32 v155, v155
	v_exp_f32_e32 v156, v156
	v_exp_f32_e32 v157, v157
	v_pk_add_f32 v[154:155], v[154:155], 1.0 op_sel_hi:[1,0]
	v_pk_add_f32 v[156:157], v[156:157], 1.0 op_sel_hi:[1,0]
	v_rcp_f32_e32 v154, v154
	v_rcp_f32_e32 v155, v155
	v_rcp_f32_e32 v156, v156
	v_rcp_f32_e32 v157, v157
	v_pk_mul_f32 v[154:155], v[92:93], v[154:155]
	v_pk_mul_f32 v[156:157], v[94:95], v[156:157]
	v_pk_mul_f32 v[154:155], v[84:85], v[154:155]
	v_pk_mul_f32 v[156:157], v[86:87], v[156:157]
	v_pk_mul_f32 v[158:159], v[88:89], s[100:101]
	v_pk_mul_f32 v[160:161], v[90:91], s[100:101]
	v_exp_f32_e32 v158, v158
	v_exp_f32_e32 v159, v159
	v_exp_f32_e32 v160, v160
	v_exp_f32_e32 v161, v161
	v_pk_add_f32 v[158:159], v[158:159], 1.0 op_sel_hi:[1,0]
	v_pk_add_f32 v[160:161], v[160:161], 1.0 op_sel_hi:[1,0]
	v_rcp_f32_e32 v158, v158
	v_rcp_f32_e32 v159, v159
	v_rcp_f32_e32 v160, v160
	v_rcp_f32_e32 v161, v161
	v_pk_mul_f32 v[158:159], v[88:89], v[158:159]
	v_pk_mul_f32 v[160:161], v[90:91], v[160:161]
	v_pk_mul_f32 v[158:159], v[82:83], v[158:159]
	v_pk_mul_f32 v[160:161], v[98:99], v[160:161]
	v_cvt_pk_bf16_f32 v80, v154, v155
	v_cvt_pk_bf16_f32 v81, v156, v157
	v_cvt_pk_bf16_f32 v82, v158, v159
	v_cvt_pk_bf16_f32 v83, v160, v161
	s_nop 0
	s_nop 0
	s_nop 0
	s_nop 0
	v_subrev_u32_e32 v84, s27, v138
	v_ashrrev_i32_e32 v85, 31, v84
	v_lshlrev_b64 v[84:85], 7, v[84:85]
	v_lshl_add_u64 v[84:85], s[38:39], 0, v[84:85]
	v_lshl_add_u64 v[84:85], v[84:85], 0, s[22:23]
	v_lshl_add_u64 v[84:85], v[84:85], 0, v[200:201]
	global_store_dwordx4 v[84:85], v[80:83], off
	s_nop 1
	v_fmamk_f32 v80, v147, 0x3a000000, v145
	v_rsq_f32_e32 v80, v80
	s_nop 0
	v_pk_mul_f32 v[76:77], v[76:77], v[80:81] op_sel_hi:[1,0]
	v_pk_mul_f32 v[82:83], v[66:67], v[80:81] op_sel_hi:[1,0]
	v_pk_mul_f32 v[66:67], v[64:65], v[80:81] op_sel_hi:[1,0]
	v_pk_mul_f32 v[68:69], v[68:69], v[80:81] op_sel_hi:[1,0]
	v_pk_mul_f32 v[78:79], v[78:79], v[80:81] op_sel_hi:[1,0]
	v_pk_mul_f32 v[70:71], v[70:71], v[80:81] op_sel_hi:[1,0]
	v_pk_mul_f32 v[72:73], v[72:73], v[80:81] op_sel_hi:[1,0]
	v_pk_mul_f32 v[74:75], v[74:75], v[80:81] op_sel_hi:[1,0]
	v_pk_mul_f32 v[154:155], v[76:77], s[100:101]
	v_pk_mul_f32 v[156:157], v[78:79], s[100:101]
	v_exp_f32_e32 v154, v154
	v_exp_f32_e32 v155, v155
	v_exp_f32_e32 v156, v156
	v_exp_f32_e32 v157, v157
	v_pk_add_f32 v[154:155], v[154:155], 1.0 op_sel_hi:[1,0]
	v_pk_add_f32 v[156:157], v[156:157], 1.0 op_sel_hi:[1,0]
	v_rcp_f32_e32 v154, v154
	v_rcp_f32_e32 v155, v155
	v_rcp_f32_e32 v156, v156
	v_rcp_f32_e32 v157, v157
	v_pk_mul_f32 v[154:155], v[76:77], v[154:155]
	v_pk_mul_f32 v[156:157], v[78:79], v[156:157]
	v_pk_mul_f32 v[154:155], v[68:69], v[154:155]
	v_pk_mul_f32 v[156:157], v[70:71], v[156:157]
	v_pk_mul_f32 v[158:159], v[72:73], s[100:101]
	v_pk_mul_f32 v[160:161], v[74:75], s[100:101]
	v_exp_f32_e32 v158, v158
	v_exp_f32_e32 v159, v159
	v_exp_f32_e32 v160, v160
	v_exp_f32_e32 v161, v161
	v_pk_add_f32 v[158:159], v[158:159], 1.0 op_sel_hi:[1,0]
	v_pk_add_f32 v[160:161], v[160:161], 1.0 op_sel_hi:[1,0]
	v_rcp_f32_e32 v158, v158
	v_rcp_f32_e32 v159, v159
	v_rcp_f32_e32 v160, v160
	v_rcp_f32_e32 v161, v161
	v_pk_mul_f32 v[158:159], v[72:73], v[158:159]
	v_pk_mul_f32 v[160:161], v[74:75], v[160:161]
	v_pk_mul_f32 v[158:159], v[66:67], v[158:159]
	v_pk_mul_f32 v[160:161], v[82:83], v[160:161]
	v_cvt_pk_bf16_f32 v64, v154, v155
	v_cvt_pk_bf16_f32 v65, v156, v157
	v_cvt_pk_bf16_f32 v66, v158, v159
	v_cvt_pk_bf16_f32 v67, v160, v161
	s_nop 0
	s_nop 0
	s_nop 0
	s_nop 0
	v_subrev_u32_e32 v68, s27, v136
	v_ashrrev_i32_e32 v69, 31, v68
	v_lshlrev_b64 v[68:69], 7, v[68:69]
	v_lshl_add_u64 v[68:69], s[38:39], 0, v[68:69]
	v_lshl_add_u64 v[68:69], v[68:69], 0, s[22:23]
	v_lshl_add_u64 v[68:69], v[68:69], 0, v[200:201]
	global_store_dwordx4 v[68:69], v[64:67], off
	s_nop 1
	v_fmamk_f32 v64, v146, 0x3a000000, v145
	v_rsq_f32_e32 v64, v64
	s_nop 0
	v_pk_mul_f32 v[60:61], v[60:61], v[64:65] op_sel_hi:[1,0]
	v_pk_mul_f32 v[66:67], v[50:51], v[64:65] op_sel_hi:[1,0]
	v_pk_mul_f32 v[50:51], v[48:49], v[64:65] op_sel_hi:[1,0]
	v_pk_mul_f32 v[52:53], v[52:53], v[64:65] op_sel_hi:[1,0]
	v_pk_mul_f32 v[62:63], v[62:63], v[64:65] op_sel_hi:[1,0]
	v_pk_mul_f32 v[54:55], v[54:55], v[64:65] op_sel_hi:[1,0]
	v_pk_mul_f32 v[56:57], v[56:57], v[64:65] op_sel_hi:[1,0]
	v_pk_mul_f32 v[58:59], v[58:59], v[64:65] op_sel_hi:[1,0]
	v_pk_mul_f32 v[154:155], v[60:61], s[100:101]
	v_pk_mul_f32 v[156:157], v[62:63], s[100:101]
	v_exp_f32_e32 v154, v154
	v_exp_f32_e32 v155, v155
	v_exp_f32_e32 v156, v156
	v_exp_f32_e32 v157, v157
	v_pk_add_f32 v[154:155], v[154:155], 1.0 op_sel_hi:[1,0]
	v_pk_add_f32 v[156:157], v[156:157], 1.0 op_sel_hi:[1,0]
	v_rcp_f32_e32 v154, v154
	v_rcp_f32_e32 v155, v155
	v_rcp_f32_e32 v156, v156
	v_rcp_f32_e32 v157, v157
	v_pk_mul_f32 v[154:155], v[60:61], v[154:155]
	v_pk_mul_f32 v[156:157], v[62:63], v[156:157]
; __device__ __forceinline__ unsigned cvt_pk_bf16(float lo, float hi) { unsigned r; asm volatile("v_cvt_pk_bf16_f32 %0, %1, %2" : "=v"(r) : "v"(lo), "v"(hi)); return r; }
; __device__ __forceinline__ float silu_mul(float g, float u) { return g * __builtin_amdgcn_rcpf(1.0f + __builtin_amdgcn_exp2f(-1.4426950408889634f * g)) * u; }
;     __device__ __forceinline__ void operator()(const f32x4 (&acc)[2][2][4][2], const Unit& u, int wr, int wc, int fr, int fq) const {
;         const int row0 = u.pm * BM + wr * 64 + fr, j0 = u.pn * HALF + wc * 32 + 8 * fq;
;         float rs[2][4];
; #pragma unroll
;         for (int ai = 0; ai < 2; ++ai)
; #pragma unroll
;             for (int m = 0; m < 4; ++m) rs[ai][m] = ss[row0 + ai * HALF + m * 16];
;         __builtin_amdgcn_sched_barrier(0);
; #pragma unroll
;         for (int ai = 0; ai < 2; ++ai)
; #pragma unroll
;             for (int m = 0; m < 4; ++m) {
;                 const int row = row0 + ai * HALF + m * 16;
;                 const float r = __builtin_amdgcn_rsqf(rs[ai][m] * (1.0f / DM) + EPSN);
;                 const f32x4 g0 = acc[ai][0][m][0] * r, g1 = acc[ai][0][m][1] * r, u0 = acc[ai][1][m][0] * r, u1 = acc[ai][1][m][1] * r;
;                 u32x4 w;
;                 w.x = cvt_pk_bf16(silu_mul(g0[0], u0[0]), silu_mul(g0[1], u0[1])); w.y = cvt_pk_bf16(silu_mul(g0[2], u0[2]), silu_mul(g0[3], u0[3]));
;                 w.z = cvt_pk_bf16(silu_mul(g1[0], u1[0]), silu_mul(g1[1], u1[1])); w.w = cvt_pk_bf16(silu_mul(g1[2], u1[2]), silu_mul(g1[3], u1[3]));
;                 *(u32x4*)(act + (((size_t)u.pm * (DFF / 64) + (u.pn * 2 + (wc >> 1))) * 256 + (row - u.pm * BM)) * 64 + (wc & 1) * 32 + 8 * fq) = w;
;                 __builtin_amdgcn_sched_barrier(0);
	v_pk_mul_f32 v[154:155], v[52:53], v[154:155]
	v_pk_mul_f32 v[156:157], v[54:55], v[156:157]
	v_pk_mul_f32 v[158:159], v[56:57], s[100:101]
	v_pk_mul_f32 v[160:161], v[58:59], s[100:101]
	v_exp_f32_e32 v158, v158
	v_exp_f32_e32 v159, v159
	v_exp_f32_e32 v160, v160
	v_exp_f32_e32 v161, v161
	v_pk_add_f32 v[158:159], v[158:159], 1.0 op_sel_hi:[1,0]
	v_pk_add_f32 v[160:161], v[160:161], 1.0 op_sel_hi:[1,0]
	v_rcp_f32_e32 v158, v158
	v_rcp_f32_e32 v159, v159
	v_rcp_f32_e32 v160, v160
	v_rcp_f32_e32 v161, v161
	v_pk_mul_f32 v[158:159], v[56:57], v[158:159]
	v_pk_mul_f32 v[160:161], v[58:59], v[160:161]
	v_pk_mul_f32 v[158:159], v[50:51], v[158:159]
	v_pk_mul_f32 v[160:161], v[66:67], v[160:161]
	v_cvt_pk_bf16_f32 v48, v154, v155
	v_cvt_pk_bf16_f32 v49, v156, v157
	v_cvt_pk_bf16_f32 v50, v158, v159
	v_cvt_pk_bf16_f32 v51, v160, v161
	v_mov_b32_e32 v53, v201
	s_nop 0
	s_nop 0
	s_nop 0
	s_nop 0
	v_add_u32_e32 v52, 0x80, v128
	v_lshlrev_b64 v[52:53], 7, v[52:53]
	v_lshl_add_u64 v[52:53], s[38:39], 0, v[52:53]
	v_lshl_add_u64 v[52:53], v[52:53], 0, s[22:23]
	v_lshl_add_u64 v[52:53], v[52:53], 0, v[200:201]
	global_store_dwordx4 v[52:53], v[48:51], off
	s_nop 1
	v_fmamk_f32 v48, v141, 0x3a000000, v145
	v_rsq_f32_e32 v48, v48
	s_nop 0
	v_pk_mul_f32 v[44:45], v[44:45], v[48:49] op_sel_hi:[1,0]
	v_pk_mul_f32 v[50:51], v[34:35], v[48:49] op_sel_hi:[1,0]
	v_pk_mul_f32 v[34:35], v[32:33], v[48:49] op_sel_hi:[1,0]
	v_pk_mul_f32 v[36:37], v[36:37], v[48:49] op_sel_hi:[1,0]
	v_pk_mul_f32 v[46:47], v[46:47], v[48:49] op_sel_hi:[1,0]
	v_pk_mul_f32 v[38:39], v[38:39], v[48:49] op_sel_hi:[1,0]
	v_pk_mul_f32 v[40:41], v[40:41], v[48:49] op_sel_hi:[1,0]
	v_pk_mul_f32 v[42:43], v[42:43], v[48:49] op_sel_hi:[1,0]
	v_pk_mul_f32 v[154:155], v[44:45], s[100:101]
	v_pk_mul_f32 v[156:157], v[46:47], s[100:101]
	v_exp_f32_e32 v154, v154
	v_exp_f32_e32 v155, v155
	v_exp_f32_e32 v156, v156
	v_exp_f32_e32 v157, v157
	v_pk_add_f32 v[154:155], v[154:155], 1.0 op_sel_hi:[1,0]
	v_pk_add_f32 v[156:157], v[156:157], 1.0 op_sel_hi:[1,0]
	v_rcp_f32_e32 v154, v154
	v_rcp_f32_e32 v155, v155
	v_rcp_f32_e32 v156, v156
	v_rcp_f32_e32 v157, v157
	v_pk_mul_f32 v[154:155], v[44:45], v[154:155]
	v_pk_mul_f32 v[156:157], v[46:47], v[156:157]
	v_pk_mul_f32 v[154:155], v[36:37], v[154:155]
	v_pk_mul_f32 v[156:157], v[38:39], v[156:157]
	v_pk_mul_f32 v[158:159], v[40:41], s[100:101]
	v_pk_mul_f32 v[160:161], v[42:43], s[100:101]
	v_exp_f32_e32 v158, v158
	v_exp_f32_e32 v159, v159
	v_exp_f32_e32 v160, v160
	v_exp_f32_e32 v161, v161
	v_pk_add_f32 v[158:159], v[158:159], 1.0 op_sel_hi:[1,0]
	v_pk_add_f32 v[160:161], v[160:161], 1.0 op_sel_hi:[1,0]
	v_rcp_f32_e32 v158, v158
	v_rcp_f32_e32 v159, v159
	v_rcp_f32_e32 v160, v160
	v_rcp_f32_e32 v161, v161
	v_pk_mul_f32 v[158:159], v[40:41], v[158:159]
	v_pk_mul_f32 v[160:161], v[42:43], v[160:161]
	v_pk_mul_f32 v[158:159], v[34:35], v[158:159]
	v_pk_mul_f32 v[160:161], v[50:51], v[160:161]
	v_cvt_pk_bf16_f32 v32, v154, v155
	v_cvt_pk_bf16_f32 v33, v156, v157
	v_cvt_pk_bf16_f32 v34, v158, v159
	v_cvt_pk_bf16_f32 v35, v160, v161
	v_mov_b32_e32 v37, v201
	s_nop 0
	s_nop 0
	s_nop 0
	s_nop 0
	v_add_u32_e32 v36, 0x90, v128
	v_lshlrev_b64 v[36:37], 7, v[36:37]
	v_lshl_add_u64 v[36:37], s[38:39], 0, v[36:37]
	v_lshl_add_u64 v[36:37], v[36:37], 0, s[22:23]
	v_lshl_add_u64 v[36:37], v[36:37], 0, v[200:201]
	global_store_dwordx4 v[36:37], v[32:35], off
	s_nop 1
	v_fmamk_f32 v32, v139, 0x3a000000, v145
	v_rsq_f32_e32 v32, v32
	s_nop 0
	v_pk_mul_f32 v[28:29], v[28:29], v[32:33] op_sel_hi:[1,0]
	v_pk_mul_f32 v[34:35], v[18:19], v[32:33] op_sel_hi:[1,0]
	v_pk_mul_f32 v[18:19], v[16:17], v[32:33] op_sel_hi:[1,0]
	v_pk_mul_f32 v[20:21], v[20:21], v[32:33] op_sel_hi:[1,0]
	v_pk_mul_f32 v[30:31], v[30:31], v[32:33] op_sel_hi:[1,0]
	v_pk_mul_f32 v[22:23], v[22:23], v[32:33] op_sel_hi:[1,0]
	v_pk_mul_f32 v[24:25], v[24:25], v[32:33] op_sel_hi:[1,0]
	v_pk_mul_f32 v[26:27], v[26:27], v[32:33] op_sel_hi:[1,0]
	v_pk_mul_f32 v[154:155], v[28:29], s[100:101]
; __device__ __forceinline__ unsigned cvt_pk_bf16(float lo, float hi) { unsigned r; asm volatile("v_cvt_pk_bf16_f32 %0, %1, %2" : "=v"(r) : "v"(lo), "v"(hi)); return r; }
; __device__ __forceinline__ float silu_mul(float g, float u) { return g * __builtin_amdgcn_rcpf(1.0f + __builtin_amdgcn_exp2f(-1.4426950408889634f * g)) * u; }
;     __device__ __forceinline__ void operator()(const f32x4 (&acc)[2][2][4][2], const Unit& u, int wr, int wc, int fr, int fq) const {
;     ...
;                 const int row = row0 + ai * HALF + m * 16;
;                 const float r = __builtin_amdgcn_rsqf(rs[ai][m] * (1.0f / DM) + EPSN);
;                 const f32x4 g0 = acc[ai][0][m][0] * r, g1 = acc[ai][0][m][1] * r, u0 = acc[ai][1][m][0] * r, u1 = acc[ai][1][m][1] * r;
;                 u32x4 w;
;                 w.x = cvt_pk_bf16(silu_mul(g0[0], u0[0]), silu_mul(g0[1], u0[1])); w.y = cvt_pk_bf16(silu_mul(g0[2], u0[2]), silu_mul(g0[3], u0[3]));
;                 w.z = cvt_pk_bf16(silu_mul(g1[0], u1[0]), silu_mul(g1[1], u1[1])); w.w = cvt_pk_bf16(silu_mul(g1[2], u1[2]), silu_mul(g1[3], u1[3]));
;                 *(u32x4*)(act + (((size_t)u.pm * (DFF / 64) + (u.pn * 2 + (wc >> 1))) * 256 + (row - u.pm * BM)) * 64 + (wc & 1) * 32 + 8 * fq) = w;
	v_pk_mul_f32 v[156:157], v[30:31], s[100:101]
	v_exp_f32_e32 v154, v154
	v_exp_f32_e32 v155, v155
	v_exp_f32_e32 v156, v156
	v_exp_f32_e32 v157, v157
	v_pk_add_f32 v[154:155], v[154:155], 1.0 op_sel_hi:[1,0]
	v_pk_add_f32 v[156:157], v[156:157], 1.0 op_sel_hi:[1,0]
	v_rcp_f32_e32 v154, v154
	v_rcp_f32_e32 v155, v155
	v_rcp_f32_e32 v156, v156
	v_rcp_f32_e32 v157, v157
	v_pk_mul_f32 v[154:155], v[28:29], v[154:155]
	v_pk_mul_f32 v[156:157], v[30:31], v[156:157]
	v_pk_mul_f32 v[154:155], v[20:21], v[154:155]
	v_pk_mul_f32 v[156:157], v[22:23], v[156:157]
	v_pk_mul_f32 v[158:159], v[24:25], s[100:101]
	v_pk_mul_f32 v[160:161], v[26:27], s[100:101]
	v_exp_f32_e32 v158, v158
	v_exp_f32_e32 v159, v159
	v_exp_f32_e32 v160, v160
	v_exp_f32_e32 v161, v161
	v_pk_add_f32 v[158:159], v[158:159], 1.0 op_sel_hi:[1,0]
	v_pk_add_f32 v[160:161], v[160:161], 1.0 op_sel_hi:[1,0]
	v_rcp_f32_e32 v158, v158
	v_rcp_f32_e32 v159, v159
	v_rcp_f32_e32 v160, v160
	v_rcp_f32_e32 v161, v161
	v_pk_mul_f32 v[158:159], v[24:25], v[158:159]
	v_pk_mul_f32 v[160:161], v[26:27], v[160:161]
	v_pk_mul_f32 v[158:159], v[18:19], v[158:159]
	v_pk_mul_f32 v[160:161], v[34:35], v[160:161]
	v_cvt_pk_bf16_f32 v16, v154, v155
	v_cvt_pk_bf16_f32 v17, v156, v157
	v_cvt_pk_bf16_f32 v18, v158, v159
	v_cvt_pk_bf16_f32 v19, v160, v161
	v_mov_b32_e32 v21, v201
	s_nop 0
	s_nop 0
	s_nop 0
	s_nop 0
	v_add_u32_e32 v20, 0xa0, v128
	v_lshlrev_b64 v[20:21], 7, v[20:21]
	v_lshl_add_u64 v[20:21], s[38:39], 0, v[20:21]
	v_lshl_add_u64 v[20:21], v[20:21], 0, s[22:23]
	v_lshl_add_u64 v[20:21], v[20:21], 0, v[200:201]
	global_store_dwordx4 v[20:21], v[16:19], off
	s_nop 1
	v_fmamk_f32 v16, v137, 0x3a000000, v145
	v_rsq_f32_e32 v16, v16
	s_nop 0
	v_pk_mul_f32 v[12:13], v[12:13], v[16:17] op_sel_hi:[1,0]
	v_pk_mul_f32 v[18:19], v[2:3], v[16:17] op_sel_hi:[1,0]
	v_pk_mul_f32 v[2:3], v[0:1], v[16:17] op_sel_hi:[1,0]
	v_pk_mul_f32 v[4:5], v[4:5], v[16:17] op_sel_hi:[1,0]
	v_pk_mul_f32 v[14:15], v[14:15], v[16:17] op_sel_hi:[1,0]
	v_pk_mul_f32 v[6:7], v[6:7], v[16:17] op_sel_hi:[1,0]
	v_pk_mul_f32 v[8:9], v[8:9], v[16:17] op_sel_hi:[1,0]
	v_pk_mul_f32 v[10:11], v[10:11], v[16:17] op_sel_hi:[1,0]
	v_pk_mul_f32 v[154:155], v[12:13], s[100:101]
	v_pk_mul_f32 v[156:157], v[14:15], s[100:101]
	v_exp_f32_e32 v154, v154
	v_exp_f32_e32 v155, v155
	v_exp_f32_e32 v156, v156
	v_exp_f32_e32 v157, v157
	v_pk_add_f32 v[154:155], v[154:155], 1.0 op_sel_hi:[1,0]
	v_pk_add_f32 v[156:157], v[156:157], 1.0 op_sel_hi:[1,0]
	v_rcp_f32_e32 v154, v154
	v_rcp_f32_e32 v155, v155
	v_rcp_f32_e32 v156, v156
	v_rcp_f32_e32 v157, v157
	v_pk_mul_f32 v[154:155], v[12:13], v[154:155]
	v_pk_mul_f32 v[156:157], v[14:15], v[156:157]
	v_pk_mul_f32 v[154:155], v[4:5], v[154:155]
	v_pk_mul_f32 v[156:157], v[6:7], v[156:157]
	v_pk_mul_f32 v[158:159], v[8:9], s[100:101]
	v_pk_mul_f32 v[160:161], v[10:11], s[100:101]
	v_exp_f32_e32 v158, v158
	v_exp_f32_e32 v159, v159
	v_exp_f32_e32 v160, v160
	v_exp_f32_e32 v161, v161
	v_pk_add_f32 v[158:159], v[158:159], 1.0 op_sel_hi:[1,0]
	v_pk_add_f32 v[160:161], v[160:161], 1.0 op_sel_hi:[1,0]
	v_rcp_f32_e32 v158, v158
	v_rcp_f32_e32 v159, v159
	v_rcp_f32_e32 v160, v160
	v_rcp_f32_e32 v161, v161
	v_pk_mul_f32 v[158:159], v[8:9], v[158:159]
	v_pk_mul_f32 v[160:161], v[10:11], v[160:161]
	v_pk_mul_f32 v[158:159], v[2:3], v[158:159]
	v_pk_mul_f32 v[160:161], v[18:19], v[160:161]
	v_cvt_pk_bf16_f32 v0, v154, v155
	v_cvt_pk_bf16_f32 v1, v156, v157
	v_cvt_pk_bf16_f32 v2, v158, v159
	v_cvt_pk_bf16_f32 v3, v160, v161
	v_mov_b32_e32 v5, v201
	s_nop 0
	s_nop 0
	s_nop 0
	s_nop 0
	v_add_u32_e32 v4, 0xb0, v128
	v_lshlrev_b64 v[4:5], 7, v[4:5]
	v_lshl_add_u64 v[4:5], s[38:39], 0, v[4:5]
	v_lshl_add_u64 v[4:5], v[4:5], 0, s[22:23]
	v_lshl_add_u64 v[4:5], v[4:5], 0, v[200:201]
	global_store_dwordx4 v[4:5], v[0:3], off
	s_andn2_b64 vcc, exec, s[30:31]
	s_mov_b64 s[30:31], -1
	s_cbranch_vccnz .LBB0_269
	s_andn2_b64 vcc, exec, s[0:1]
	s_cbranch_vccnz .LBB0_268
	s_barrier
	s_branch .LBB0_268

; __device__ __forceinline__ unsigned cvt_pk_bf16(float lo, float hi) { unsigned r; asm volatile("v_cvt_pk_bf16_f32 %0, %1, %2" : "=v"(r) : "v"(lo), "v"(hi)); return r; }
; __device__ __forceinline__ float silu_mul(float g, float u) { return g * __builtin_amdgcn_rcpf(1.0f + __builtin_amdgcn_exp2f(-1.4426950408889634f * g)) * u; }
;     __device__ __forceinline__ void operator()(const f32x4 (&acc)[2][2][4][2], const Unit& u, int wr, int wc, int fr, int fq) const {
;         const int row0 = u.pm * BM + wr * 64 + fr, j0 = u.pn * HALF + wc * 32 + 8 * fq;
;         float rs[2][4];
; #pragma unroll
;         for (int ai = 0; ai < 2; ++ai)
; #pragma unroll
;             for (int m = 0; m < 4; ++m) rs[ai][m] = ss[row0 + ai * HALF + m * 16];
;         __builtin_amdgcn_sched_barrier(0);
; #pragma unroll
;         for (int ai = 0; ai < 2; ++ai)
; #pragma unroll
;             for (int m = 0; m < 4; ++m) {
;                 const int row = row0 + ai * HALF + m * 16;
;                 const float r = __builtin_amdgcn_rsqf(rs[ai][m] * (1.0f / DM) + EPSN);
;                 const f32x4 g0 = acc[ai][0][m][0] * r, g1 = acc[ai][0][m][1] * r, u0 = acc[ai][1][m][0] * r, u1 = acc[ai][1][m][1] * r;
;                 u32x4 w;
;                 w.x = cvt_pk_bf16(silu_mul(g0[0], u0[0]), silu_mul(g0[1], u0[1])); w.y = cvt_pk_bf16(silu_mul(g0[2], u0[2]), silu_mul(g0[3], u0[3]));
;                 w.z = cvt_pk_bf16(silu_mul(g1[0], u1[0]), silu_mul(g1[1], u1[1])); w.w = cvt_pk_bf16(silu_mul(g1[2], u1[2]), silu_mul(g1[3], u1[3]));
;                 *(u32x4*)(act + (((size_t)u.pm * (DFF / 64) + (u.pn * 2 + (wc >> 1))) * 256 + (row - u.pm * BM)) * 64 + (wc & 1) * 32 + 8 * fq) = w;
.LBB0_1342:
	s_lshl_b32 s21, s30, 8
	v_add_u32_e32 v136, s21, v128
	v_ashrrev_i32_e32 v137, 31, v136
	v_lshl_add_u64 v[146:147], v[136:137], 2, s[76:77]
	v_or_b32_e32 v148, 16, v136
	v_or_b32_e32 v138, 32, v136
	v_or_b32_e32 v136, 48, v136
	v_ashrrev_i32_e32 v149, 31, v148
	v_ashrrev_i32_e32 v137, 31, v136
	v_lshl_add_u64 v[144:145], v[148:149], 2, s[76:77]
	v_ashrrev_i32_e32 v139, 31, v138
	v_lshl_add_u64 v[152:153], v[136:137], 2, s[76:77]
	v_lshl_add_u64 v[150:151], v[138:139], 2, s[76:77]
	global_load_dword v149, v[146:147], off
	s_nop 0
	global_load_dword v145, v[144:145], off
	s_nop 0
	global_load_dword v154, v[150:151], off
	s_nop 0
	global_load_dword v152, v[152:153], off
	s_nop 0
	global_load_dword v153, v[146:147], off offset:512
	global_load_dword v144, v[146:147], off offset:576
	global_load_dword v139, v[146:147], off offset:640
	global_load_dword v137, v[146:147], off offset:704
	s_waitcnt vmcnt(0)
	s_mov_b32 s100, 0xbfb8aa3b
	s_mov_b32 s101, 0xbfb8aa3b
	v_fmamk_f32 v146, v149, 0x3a000000, v143
	v_rsq_f32_e32 v146, v146
	s_lshl_b32 s31, s31, 1
	s_or_b32 s31, s31, s45
	s_mul_hi_i32 s23, s30, 0x56
	v_pk_mul_f32 v[124:125], v[124:125], v[146:147] op_sel_hi:[1,0]
	v_pk_mul_f32 v[126:127], v[126:127], v[146:147] op_sel_hi:[1,0]
	v_pk_mul_f32 v[122:123], v[122:123], v[146:147] op_sel_hi:[1,0]
	v_pk_mul_f32 v[120:121], v[120:121], v[146:147] op_sel_hi:[1,0]
	v_pk_mul_f32 v[118:119], v[118:119], v[146:147] op_sel_hi:[1,0]
	v_pk_mul_f32 v[116:117], v[116:117], v[146:147] op_sel_hi:[1,0]
	s_mulk_i32 s30, 0x56
	v_pk_mul_f32 v[150:151], v[114:115], v[146:147] op_sel_hi:[1,0]
	s_ashr_i32 s34, s31, 31
	v_pk_mul_f32 v[114:115], v[112:113], v[146:147] op_sel_hi:[1,0]
	v_pk_mul_f32 v[156:157], v[124:125], s[100:101]
	v_pk_mul_f32 v[158:159], v[126:127], s[100:101]
	v_exp_f32_e32 v156, v156
	v_exp_f32_e32 v157, v157
	v_exp_f32_e32 v158, v158
	v_exp_f32_e32 v159, v159
	v_pk_add_f32 v[156:157], v[156:157], 1.0 op_sel_hi:[1,0]
	v_pk_add_f32 v[158:159], v[158:159], 1.0 op_sel_hi:[1,0]
	v_rcp_f32_e32 v156, v156
	v_rcp_f32_e32 v157, v157
	v_rcp_f32_e32 v158, v158
	v_rcp_f32_e32 v159, v159
	v_pk_mul_f32 v[156:157], v[124:125], v[156:157]
	v_pk_mul_f32 v[158:159], v[126:127], v[158:159]
	v_pk_mul_f32 v[156:157], v[116:117], v[156:157]
	v_pk_mul_f32 v[158:159], v[118:119], v[158:159]
	v_pk_mul_f32 v[160:161], v[120:121], s[100:101]
	v_pk_mul_f32 v[162:163], v[122:123], s[100:101]
	v_exp_f32_e32 v160, v160
	v_exp_f32_e32 v161, v161
	v_exp_f32_e32 v162, v162
	v_exp_f32_e32 v163, v163
	v_pk_add_f32 v[160:161], v[160:161], 1.0 op_sel_hi:[1,0]
	v_pk_add_f32 v[162:163], v[162:163], 1.0 op_sel_hi:[1,0]
	v_rcp_f32_e32 v160, v160
	v_rcp_f32_e32 v161, v161
	v_rcp_f32_e32 v162, v162
	v_rcp_f32_e32 v163, v163
	v_pk_mul_f32 v[160:161], v[120:121], v[160:161]
	v_pk_mul_f32 v[162:163], v[122:123], v[162:163]
	v_pk_mul_f32 v[160:161], v[114:115], v[160:161]
	v_pk_mul_f32 v[162:163], v[150:151], v[162:163]
	v_cvt_pk_bf16_f32 v112, v156, v157
	v_cvt_pk_bf16_f32 v113, v158, v159
	v_cvt_pk_bf16_f32 v114, v160, v161
	v_cvt_pk_bf16_f32 v115, v162, v163
	s_add_u32 s30, s30, s31
	s_addc_u32 s31, s23, s34
	s_lshl_b64 s[30:31], s[30:31], 15
	s_add_u32 s30, s4, s30
	s_addc_u32 s31, s5, s31
	v_lshl_add_u64 v[116:117], s[30:31], 0, v[130:131]
	v_lshl_add_u64 v[116:117], v[116:117], 0, s[16:17]
	v_lshl_add_u64 v[116:117], v[116:117], 0, v[200:201]
	global_store_dwordx4 v[116:117], v[112:115], off
	s_nop 1
	v_fmamk_f32 v112, v145, 0x3a000000, v143
	v_rsq_f32_e32 v112, v112
	s_nop 0
	v_pk_mul_f32 v[108:109], v[108:109], v[112:113] op_sel_hi:[1,0]
	v_pk_mul_f32 v[110:111], v[110:111], v[112:113] op_sel_hi:[1,0]
	v_pk_mul_f32 v[106:107], v[106:107], v[112:113] op_sel_hi:[1,0]
	v_pk_mul_f32 v[104:105], v[104:105], v[112:113] op_sel_hi:[1,0]
	v_pk_mul_f32 v[102:103], v[102:103], v[112:113] op_sel_hi:[1,0]
	v_pk_mul_f32 v[100:101], v[100:101], v[112:113] op_sel_hi:[1,0]
	v_pk_mul_f32 v[114:115], v[98:99], v[112:113] op_sel_hi:[1,0]
	v_pk_mul_f32 v[98:99], v[96:97], v[112:113] op_sel_hi:[1,0]
	v_pk_mul_f32 v[156:157], v[108:109], s[100:101]
	v_pk_mul_f32 v[158:159], v[110:111], s[100:101]
	v_exp_f32_e32 v156, v156
	v_exp_f32_e32 v157, v157
	v_exp_f32_e32 v158, v158
	v_exp_f32_e32 v159, v159
	v_pk_add_f32 v[156:157], v[156:157], 1.0 op_sel_hi:[1,0]
	v_pk_add_f32 v[158:159], v[158:159], 1.0 op_sel_hi:[1,0]
	v_rcp_f32_e32 v156, v156
	v_rcp_f32_e32 v157, v157
	v_rcp_f32_e32 v158, v158
	v_rcp_f32_e32 v159, v159
	v_pk_mul_f32 v[156:157], v[108:109], v[156:157]
	v_pk_mul_f32 v[158:159], v[110:111], v[158:159]
	v_pk_mul_f32 v[156:157], v[100:101], v[156:157]
	v_pk_mul_f32 v[158:159], v[102:103], v[158:159]
	v_pk_mul_f32 v[160:161], v[104:105], s[100:101]
	v_pk_mul_f32 v[162:163], v[106:107], s[100:101]
	v_exp_f32_e32 v160, v160
	v_exp_f32_e32 v161, v161
	v_exp_f32_e32 v162, v162
	v_exp_f32_e32 v163, v163
	v_pk_add_f32 v[160:161], v[160:161], 1.0 op_sel_hi:[1,0]
	v_pk_add_f32 v[162:163], v[162:163], 1.0 op_sel_hi:[1,0]
	v_rcp_f32_e32 v160, v160
	v_rcp_f32_e32 v161, v161
	v_rcp_f32_e32 v162, v162
	v_rcp_f32_e32 v163, v163
	v_pk_mul_f32 v[160:161], v[104:105], v[160:161]
	v_pk_mul_f32 v[162:163], v[106:107], v[162:163]
	v_pk_mul_f32 v[160:161], v[98:99], v[160:161]
	v_pk_mul_f32 v[162:163], v[114:115], v[162:163]
	v_cvt_pk_bf16_f32 v96, v156, v157
	v_cvt_pk_bf16_f32 v97, v158, v159
	v_cvt_pk_bf16_f32 v98, v160, v161
	v_cvt_pk_bf16_f32 v99, v162, v163
	v_subrev_u32_e32 v100, s21, v148
	v_ashrrev_i32_e32 v101, 31, v100
	v_lshlrev_b64 v[100:101], 7, v[100:101]
	v_lshl_add_u64 v[100:101], s[30:31], 0, v[100:101]
	v_lshl_add_u64 v[100:101], v[100:101], 0, s[16:17]
	v_lshl_add_u64 v[100:101], v[100:101], 0, v[200:201]
; __device__ __forceinline__ unsigned cvt_pk_bf16(float lo, float hi) { unsigned r; asm volatile("v_cvt_pk_bf16_f32 %0, %1, %2" : "=v"(r) : "v"(lo), "v"(hi)); return r; }
; __device__ __forceinline__ float silu_mul(float g, float u) { return g * __builtin_amdgcn_rcpf(1.0f + __builtin_amdgcn_exp2f(-1.4426950408889634f * g)) * u; }
;     __device__ __forceinline__ void operator()(const f32x4 (&acc)[2][2][4][2], const Unit& u, int wr, int wc, int fr, int fq) const {
;     ...
;             for (int m = 0; m < 4; ++m) {
;                 const int row = row0 + ai * HALF + m * 16;
;                 const float r = __builtin_amdgcn_rsqf(rs[ai][m] * (1.0f / DM) + EPSN);
;                 const f32x4 g0 = acc[ai][0][m][0] * r, g1 = acc[ai][0][m][1] * r, u0 = acc[ai][1][m][0] * r, u1 = acc[ai][1][m][1] * r;
;                 u32x4 w;
;                 w.x = cvt_pk_bf16(silu_mul(g0[0], u0[0]), silu_mul(g0[1], u0[1])); w.y = cvt_pk_bf16(silu_mul(g0[2], u0[2]), silu_mul(g0[3], u0[3]));
;                 w.z = cvt_pk_bf16(silu_mul(g1[0], u1[0]), silu_mul(g1[1], u1[1])); w.w = cvt_pk_bf16(silu_mul(g1[2], u1[2]), silu_mul(g1[3], u1[3]));
;                 *(u32x4*)(act + (((size_t)u.pm * (DFF / 64) + (u.pn * 2 + (wc >> 1))) * 256 + (row - u.pm * BM)) * 64 + (wc & 1) * 32 + 8 * fq) = w;
	global_store_dwordx4 v[100:101], v[96:99], off
	s_nop 1
	v_fmamk_f32 v96, v154, 0x3a000000, v143
	v_rsq_f32_e32 v96, v96
	s_nop 0
	v_pk_mul_f32 v[92:93], v[92:93], v[96:97] op_sel_hi:[1,0]
	v_pk_mul_f32 v[94:95], v[94:95], v[96:97] op_sel_hi:[1,0]
	v_pk_mul_f32 v[90:91], v[90:91], v[96:97] op_sel_hi:[1,0]
	v_pk_mul_f32 v[88:89], v[88:89], v[96:97] op_sel_hi:[1,0]
	v_pk_mul_f32 v[86:87], v[86:87], v[96:97] op_sel_hi:[1,0]
	v_pk_mul_f32 v[84:85], v[84:85], v[96:97] op_sel_hi:[1,0]
	v_pk_mul_f32 v[98:99], v[82:83], v[96:97] op_sel_hi:[1,0]
	v_pk_mul_f32 v[82:83], v[80:81], v[96:97] op_sel_hi:[1,0]
	v_pk_mul_f32 v[156:157], v[92:93], s[100:101]
	v_pk_mul_f32 v[158:159], v[94:95], s[100:101]
	v_exp_f32_e32 v156, v156
	v_exp_f32_e32 v157, v157
	v_exp_f32_e32 v158, v158
	v_exp_f32_e32 v159, v159
	v_pk_add_f32 v[156:157], v[156:157], 1.0 op_sel_hi:[1,0]
	v_pk_add_f32 v[158:159], v[158:159], 1.0 op_sel_hi:[1,0]
	v_rcp_f32_e32 v156, v156
	v_rcp_f32_e32 v157, v157
	v_rcp_f32_e32 v158, v158
	v_rcp_f32_e32 v159, v159
	v_pk_mul_f32 v[156:157], v[92:93], v[156:157]
	v_pk_mul_f32 v[158:159], v[94:95], v[158:159]
	v_pk_mul_f32 v[156:157], v[84:85], v[156:157]
	v_pk_mul_f32 v[158:159], v[86:87], v[158:159]
	v_pk_mul_f32 v[160:161], v[88:89], s[100:101]
	v_pk_mul_f32 v[162:163], v[90:91], s[100:101]
	v_exp_f32_e32 v160, v160
	v_exp_f32_e32 v161, v161
	v_exp_f32_e32 v162, v162
	v_exp_f32_e32 v163, v163
	v_pk_add_f32 v[160:161], v[160:161], 1.0 op_sel_hi:[1,0]
	v_pk_add_f32 v[162:163], v[162:163], 1.0 op_sel_hi:[1,0]
	v_rcp_f32_e32 v160, v160
	v_rcp_f32_e32 v161, v161
	v_rcp_f32_e32 v162, v162
	v_rcp_f32_e32 v163, v163
	v_pk_mul_f32 v[160:161], v[88:89], v[160:161]
	v_pk_mul_f32 v[162:163], v[90:91], v[162:163]
	v_pk_mul_f32 v[160:161], v[82:83], v[160:161]
	v_pk_mul_f32 v[162:163], v[98:99], v[162:163]
	v_cvt_pk_bf16_f32 v80, v156, v157
	v_cvt_pk_bf16_f32 v81, v158, v159
	v_cvt_pk_bf16_f32 v82, v160, v161
	v_cvt_pk_bf16_f32 v83, v162, v163
	v_subrev_u32_e32 v84, s21, v138
	v_ashrrev_i32_e32 v85, 31, v84
	v_lshlrev_b64 v[84:85], 7, v[84:85]
	v_lshl_add_u64 v[84:85], s[30:31], 0, v[84:85]
	v_lshl_add_u64 v[84:85], v[84:85], 0, s[16:17]
	v_lshl_add_u64 v[84:85], v[84:85], 0, v[200:201]
	global_store_dwordx4 v[84:85], v[80:83], off
	s_nop 1
	v_fmamk_f32 v80, v152, 0x3a000000, v143
	v_rsq_f32_e32 v80, v80
	s_nop 0
	v_pk_mul_f32 v[76:77], v[76:77], v[80:81] op_sel_hi:[1,0]
	v_pk_mul_f32 v[78:79], v[78:79], v[80:81] op_sel_hi:[1,0]
	v_pk_mul_f32 v[74:75], v[74:75], v[80:81] op_sel_hi:[1,0]
	v_pk_mul_f32 v[72:73], v[72:73], v[80:81] op_sel_hi:[1,0]
	v_pk_mul_f32 v[70:71], v[70:71], v[80:81] op_sel_hi:[1,0]
	v_pk_mul_f32 v[68:69], v[68:69], v[80:81] op_sel_hi:[1,0]
	v_pk_mul_f32 v[82:83], v[66:67], v[80:81] op_sel_hi:[1,0]
	v_pk_mul_f32 v[66:67], v[64:65], v[80:81] op_sel_hi:[1,0]
	v_pk_mul_f32 v[156:157], v[76:77], s[100:101]
	v_pk_mul_f32 v[158:159], v[78:79], s[100:101]
	v_exp_f32_e32 v156, v156
	v_exp_f32_e32 v157, v157
	v_exp_f32_e32 v158, v158
	v_exp_f32_e32 v159, v159
	v_pk_add_f32 v[156:157], v[156:157], 1.0 op_sel_hi:[1,0]
	v_pk_add_f32 v[158:159], v[158:159], 1.0 op_sel_hi:[1,0]
	v_rcp_f32_e32 v156, v156
	v_rcp_f32_e32 v157, v157
	v_rcp_f32_e32 v158, v158
	v_rcp_f32_e32 v159, v159
	v_pk_mul_f32 v[156:157], v[76:77], v[156:157]
	v_pk_mul_f32 v[158:159], v[78:79], v[158:159]
	v_pk_mul_f32 v[156:157], v[68:69], v[156:157]
	v_pk_mul_f32 v[158:159], v[70:71], v[158:159]
	v_pk_mul_f32 v[160:161], v[72:73], s[100:101]
	v_pk_mul_f32 v[162:163], v[74:75], s[100:101]
	v_exp_f32_e32 v160, v160
	v_exp_f32_e32 v161, v161
	v_exp_f32_e32 v162, v162
	v_exp_f32_e32 v163, v163
	v_pk_add_f32 v[160:161], v[160:161], 1.0 op_sel_hi:[1,0]
	v_pk_add_f32 v[162:163], v[162:163], 1.0 op_sel_hi:[1,0]
	v_rcp_f32_e32 v160, v160
	v_rcp_f32_e32 v161, v161
	v_rcp_f32_e32 v162, v162
	v_rcp_f32_e32 v163, v163
	v_pk_mul_f32 v[160:161], v[72:73], v[160:161]
	v_pk_mul_f32 v[162:163], v[74:75], v[162:163]
	v_pk_mul_f32 v[160:161], v[66:67], v[160:161]
	v_pk_mul_f32 v[162:163], v[82:83], v[162:163]
	v_cvt_pk_bf16_f32 v64, v156, v157
	v_cvt_pk_bf16_f32 v65, v158, v159
	v_cvt_pk_bf16_f32 v66, v160, v161
	v_cvt_pk_bf16_f32 v67, v162, v163
	v_subrev_u32_e32 v68, s21, v136
	v_ashrrev_i32_e32 v69, 31, v68
	v_lshlrev_b64 v[68:69], 7, v[68:69]
	v_lshl_add_u64 v[68:69], s[30:31], 0, v[68:69]
	v_lshl_add_u64 v[68:69], v[68:69], 0, s[16:17]
	v_lshl_add_u64 v[68:69], v[68:69], 0, v[200:201]
	global_store_dwordx4 v[68:69], v[64:67], off
	s_nop 1
	v_fmamk_f32 v64, v153, 0x3a000000, v143
	v_rsq_f32_e32 v64, v64
	s_nop 0
	v_pk_mul_f32 v[60:61], v[60:61], v[64:65] op_sel_hi:[1,0]
	v_pk_mul_f32 v[62:63], v[62:63], v[64:65] op_sel_hi:[1,0]
	v_pk_mul_f32 v[58:59], v[58:59], v[64:65] op_sel_hi:[1,0]
	v_pk_mul_f32 v[56:57], v[56:57], v[64:65] op_sel_hi:[1,0]
	v_pk_mul_f32 v[54:55], v[54:55], v[64:65] op_sel_hi:[1,0]
	v_pk_mul_f32 v[52:53], v[52:53], v[64:65] op_sel_hi:[1,0]
	v_pk_mul_f32 v[66:67], v[50:51], v[64:65] op_sel_hi:[1,0]
	v_pk_mul_f32 v[50:51], v[48:49], v[64:65] op_sel_hi:[1,0]
	v_pk_mul_f32 v[156:157], v[60:61], s[100:101]
	v_pk_mul_f32 v[158:159], v[62:63], s[100:101]
	v_exp_f32_e32 v156, v156
	v_exp_f32_e32 v157, v157
	v_exp_f32_e32 v158, v158
	v_exp_f32_e32 v159, v159
	v_pk_add_f32 v[156:157], v[156:157], 1.0 op_sel_hi:[1,0]
	v_pk_add_f32 v[158:159], v[158:159], 1.0 op_sel_hi:[1,0]
	v_rcp_f32_e32 v156, v156
	v_rcp_f32_e32 v157, v157
	v_rcp_f32_e32 v158, v158
	v_rcp_f32_e32 v159, v159
	v_pk_mul_f32 v[156:157], v[60:61], v[156:157]
	v_pk_mul_f32 v[158:159], v[62:63], v[158:159]
	v_pk_mul_f32 v[156:157], v[52:53], v[156:157]
	v_pk_mul_f32 v[158:159], v[54:55], v[158:159]
	v_pk_mul_f32 v[160:161], v[56:57], s[100:101]
; __device__ __forceinline__ unsigned cvt_pk_bf16(float lo, float hi) { unsigned r; asm volatile("v_cvt_pk_bf16_f32 %0, %1, %2" : "=v"(r) : "v"(lo), "v"(hi)); return r; }
; __device__ __forceinline__ float silu_mul(float g, float u) { return g * __builtin_amdgcn_rcpf(1.0f + __builtin_amdgcn_exp2f(-1.4426950408889634f * g)) * u; }
;     __device__ __forceinline__ void operator()(const f32x4 (&acc)[2][2][4][2], const Unit& u, int wr, int wc, int fr, int fq) const {
;     ...
;             for (int m = 0; m < 4; ++m) {
;                 const int row = row0 + ai * HALF + m * 16;
;                 const float r = __builtin_amdgcn_rsqf(rs[ai][m] * (1.0f / DM) + EPSN);
;                 const f32x4 g0 = acc[ai][0][m][0] * r, g1 = acc[ai][0][m][1] * r, u0 = acc[ai][1][m][0] * r, u1 = acc[ai][1][m][1] * r;
;                 u32x4 w;
;                 w.x = cvt_pk_bf16(silu_mul(g0[0], u0[0]), silu_mul(g0[1], u0[1])); w.y = cvt_pk_bf16(silu_mul(g0[2], u0[2]), silu_mul(g0[3], u0[3]));
;                 w.z = cvt_pk_bf16(silu_mul(g1[0], u1[0]), silu_mul(g1[1], u1[1])); w.w = cvt_pk_bf16(silu_mul(g1[2], u1[2]), silu_mul(g1[3], u1[3]));
;                 *(u32x4*)(act + (((size_t)u.pm * (DFF / 64) + (u.pn * 2 + (wc >> 1))) * 256 + (row - u.pm * BM)) * 64 + (wc & 1) * 32 + 8 * fq) = w;
	v_pk_mul_f32 v[162:163], v[58:59], s[100:101]
	v_exp_f32_e32 v160, v160
	v_exp_f32_e32 v161, v161
	v_exp_f32_e32 v162, v162
	v_exp_f32_e32 v163, v163
	v_pk_add_f32 v[160:161], v[160:161], 1.0 op_sel_hi:[1,0]
	v_pk_add_f32 v[162:163], v[162:163], 1.0 op_sel_hi:[1,0]
	v_rcp_f32_e32 v160, v160
	v_rcp_f32_e32 v161, v161
	v_rcp_f32_e32 v162, v162
	v_rcp_f32_e32 v163, v163
	v_pk_mul_f32 v[160:161], v[56:57], v[160:161]
	v_pk_mul_f32 v[162:163], v[58:59], v[162:163]
	v_pk_mul_f32 v[160:161], v[50:51], v[160:161]
	v_pk_mul_f32 v[162:163], v[66:67], v[162:163]
	v_cvt_pk_bf16_f32 v48, v156, v157
	v_cvt_pk_bf16_f32 v49, v158, v159
	v_cvt_pk_bf16_f32 v50, v160, v161
	v_cvt_pk_bf16_f32 v51, v162, v163
	v_add_u32_e32 v52, 0x80, v128
	v_mov_b32_e32 v53, v201
	v_lshlrev_b64 v[52:53], 7, v[52:53]
	v_lshl_add_u64 v[52:53], s[30:31], 0, v[52:53]
	v_lshl_add_u64 v[52:53], v[52:53], 0, s[16:17]
	v_lshl_add_u64 v[52:53], v[52:53], 0, v[200:201]
	global_store_dwordx4 v[52:53], v[48:51], off
	s_nop 1
	v_fmamk_f32 v48, v144, 0x3a000000, v143
	v_rsq_f32_e32 v48, v48
	s_nop 0
	v_pk_mul_f32 v[44:45], v[44:45], v[48:49] op_sel_hi:[1,0]
	v_pk_mul_f32 v[46:47], v[46:47], v[48:49] op_sel_hi:[1,0]
	v_pk_mul_f32 v[42:43], v[42:43], v[48:49] op_sel_hi:[1,0]
	v_pk_mul_f32 v[40:41], v[40:41], v[48:49] op_sel_hi:[1,0]
	v_pk_mul_f32 v[38:39], v[38:39], v[48:49] op_sel_hi:[1,0]
	v_pk_mul_f32 v[36:37], v[36:37], v[48:49] op_sel_hi:[1,0]
	v_pk_mul_f32 v[50:51], v[34:35], v[48:49] op_sel_hi:[1,0]
	v_pk_mul_f32 v[34:35], v[32:33], v[48:49] op_sel_hi:[1,0]
	v_pk_mul_f32 v[156:157], v[44:45], s[100:101]
	v_pk_mul_f32 v[158:159], v[46:47], s[100:101]
	v_exp_f32_e32 v156, v156
	v_exp_f32_e32 v157, v157
	v_exp_f32_e32 v158, v158
	v_exp_f32_e32 v159, v159
	v_pk_add_f32 v[156:157], v[156:157], 1.0 op_sel_hi:[1,0]
	v_pk_add_f32 v[158:159], v[158:159], 1.0 op_sel_hi:[1,0]
	v_rcp_f32_e32 v156, v156
	v_rcp_f32_e32 v157, v157
	v_rcp_f32_e32 v158, v158
	v_rcp_f32_e32 v159, v159
	v_pk_mul_f32 v[156:157], v[44:45], v[156:157]
	v_pk_mul_f32 v[158:159], v[46:47], v[158:159]
	v_pk_mul_f32 v[156:157], v[36:37], v[156:157]
	v_pk_mul_f32 v[158:159], v[38:39], v[158:159]
	v_pk_mul_f32 v[160:161], v[40:41], s[100:101]
	v_pk_mul_f32 v[162:163], v[42:43], s[100:101]
	v_exp_f32_e32 v160, v160
	v_exp_f32_e32 v161, v161
	v_exp_f32_e32 v162, v162
	v_exp_f32_e32 v163, v163
	v_pk_add_f32 v[160:161], v[160:161], 1.0 op_sel_hi:[1,0]
	v_pk_add_f32 v[162:163], v[162:163], 1.0 op_sel_hi:[1,0]
	v_rcp_f32_e32 v160, v160
	v_rcp_f32_e32 v161, v161
	v_rcp_f32_e32 v162, v162
	v_rcp_f32_e32 v163, v163
	v_pk_mul_f32 v[160:161], v[40:41], v[160:161]
	v_pk_mul_f32 v[162:163], v[42:43], v[162:163]
	v_pk_mul_f32 v[160:161], v[34:35], v[160:161]
	v_pk_mul_f32 v[162:163], v[50:51], v[162:163]
	v_cvt_pk_bf16_f32 v32, v156, v157
	v_cvt_pk_bf16_f32 v33, v158, v159
	v_cvt_pk_bf16_f32 v34, v160, v161
	v_cvt_pk_bf16_f32 v35, v162, v163
	v_add_u32_e32 v36, 0x90, v128
	v_mov_b32_e32 v37, v201
	v_lshlrev_b64 v[36:37], 7, v[36:37]
	v_lshl_add_u64 v[36:37], s[30:31], 0, v[36:37]
	v_lshl_add_u64 v[36:37], v[36:37], 0, s[16:17]
	v_lshl_add_u64 v[36:37], v[36:37], 0, v[200:201]
	global_store_dwordx4 v[36:37], v[32:35], off
	s_nop 1
	v_fmamk_f32 v32, v139, 0x3a000000, v143
	v_rsq_f32_e32 v32, v32
	s_nop 0
	v_pk_mul_f32 v[28:29], v[28:29], v[32:33] op_sel_hi:[1,0]
	v_pk_mul_f32 v[30:31], v[30:31], v[32:33] op_sel_hi:[1,0]
	v_pk_mul_f32 v[26:27], v[26:27], v[32:33] op_sel_hi:[1,0]
	v_pk_mul_f32 v[24:25], v[24:25], v[32:33] op_sel_hi:[1,0]
	v_pk_mul_f32 v[22:23], v[22:23], v[32:33] op_sel_hi:[1,0]
	v_pk_mul_f32 v[20:21], v[20:21], v[32:33] op_sel_hi:[1,0]
	v_pk_mul_f32 v[34:35], v[18:19], v[32:33] op_sel_hi:[1,0]
	v_pk_mul_f32 v[18:19], v[16:17], v[32:33] op_sel_hi:[1,0]
	v_pk_mul_f32 v[156:157], v[28:29], s[100:101]
	v_pk_mul_f32 v[158:159], v[30:31], s[100:101]
	v_exp_f32_e32 v156, v156
; __device__ __forceinline__ unsigned cvt_pk_bf16(float lo, float hi) { unsigned r; asm volatile("v_cvt_pk_bf16_f32 %0, %1, %2" : "=v"(r) : "v"(lo), "v"(hi)); return r; }
; __device__ __forceinline__ float silu_mul(float g, float u) { return g * __builtin_amdgcn_rcpf(1.0f + __builtin_amdgcn_exp2f(-1.4426950408889634f * g)) * u; }
;     __device__ __forceinline__ void operator()(const f32x4 (&acc)[2][2][4][2], const Unit& u, int wr, int wc, int fr, int fq) const {
;     ...
;             for (int m = 0; m < 4; ++m) {
;                 const int row = row0 + ai * HALF + m * 16;
;                 const float r = __builtin_amdgcn_rsqf(rs[ai][m] * (1.0f / DM) + EPSN);
;                 const f32x4 g0 = acc[ai][0][m][0] * r, g1 = acc[ai][0][m][1] * r, u0 = acc[ai][1][m][0] * r, u1 = acc[ai][1][m][1] * r;
;                 u32x4 w;
;                 w.x = cvt_pk_bf16(silu_mul(g0[0], u0[0]), silu_mul(g0[1], u0[1])); w.y = cvt_pk_bf16(silu_mul(g0[2], u0[2]), silu_mul(g0[3], u0[3]));
;                 w.z = cvt_pk_bf16(silu_mul(g1[0], u1[0]), silu_mul(g1[1], u1[1])); w.w = cvt_pk_bf16(silu_mul(g1[2], u1[2]), silu_mul(g1[3], u1[3]));
;                 *(u32x4*)(act + (((size_t)u.pm * (DFF / 64) + (u.pn * 2 + (wc >> 1))) * 256 + (row - u.pm * BM)) * 64 + (wc & 1) * 32 + 8 * fq) = w;
	v_exp_f32_e32 v157, v157
	v_exp_f32_e32 v158, v158
	v_exp_f32_e32 v159, v159
	v_pk_add_f32 v[156:157], v[156:157], 1.0 op_sel_hi:[1,0]
	v_pk_add_f32 v[158:159], v[158:159], 1.0 op_sel_hi:[1,0]
	v_rcp_f32_e32 v156, v156
	v_rcp_f32_e32 v157, v157
	v_rcp_f32_e32 v158, v158
	v_rcp_f32_e32 v159, v159
	v_pk_mul_f32 v[156:157], v[28:29], v[156:157]
	v_pk_mul_f32 v[158:159], v[30:31], v[158:159]
	v_pk_mul_f32 v[156:157], v[20:21], v[156:157]
	v_pk_mul_f32 v[158:159], v[22:23], v[158:159]
	v_pk_mul_f32 v[160:161], v[24:25], s[100:101]
	v_pk_mul_f32 v[162:163], v[26:27], s[100:101]
	v_exp_f32_e32 v160, v160
	v_exp_f32_e32 v161, v161
	v_exp_f32_e32 v162, v162
	v_exp_f32_e32 v163, v163
	v_pk_add_f32 v[160:161], v[160:161], 1.0 op_sel_hi:[1,0]
	v_pk_add_f32 v[162:163], v[162:163], 1.0 op_sel_hi:[1,0]
	v_rcp_f32_e32 v160, v160
	v_rcp_f32_e32 v161, v161
	v_rcp_f32_e32 v162, v162
	v_rcp_f32_e32 v163, v163
	v_pk_mul_f32 v[160:161], v[24:25], v[160:161]
	v_pk_mul_f32 v[162:163], v[26:27], v[162:163]
	v_pk_mul_f32 v[160:161], v[18:19], v[160:161]
	v_pk_mul_f32 v[162:163], v[34:35], v[162:163]
	v_cvt_pk_bf16_f32 v16, v156, v157
	v_cvt_pk_bf16_f32 v17, v158, v159
	v_cvt_pk_bf16_f32 v18, v160, v161
	v_cvt_pk_bf16_f32 v19, v162, v163
	v_add_u32_e32 v20, 0xa0, v128
	v_mov_b32_e32 v21, v201
	v_lshlrev_b64 v[20:21], 7, v[20:21]
	v_lshl_add_u64 v[20:21], s[30:31], 0, v[20:21]
	v_lshl_add_u64 v[20:21], v[20:21], 0, s[16:17]
	v_lshl_add_u64 v[20:21], v[20:21], 0, v[200:201]
	global_store_dwordx4 v[20:21], v[16:19], off
	s_nop 1
	v_fmamk_f32 v16, v137, 0x3a000000, v143
	v_rsq_f32_e32 v16, v16
	s_nop 0
	v_pk_mul_f32 v[12:13], v[12:13], v[16:17] op_sel_hi:[1,0]
	v_pk_mul_f32 v[14:15], v[14:15], v[16:17] op_sel_hi:[1,0]
	v_pk_mul_f32 v[10:11], v[10:11], v[16:17] op_sel_hi:[1,0]
	v_pk_mul_f32 v[8:9], v[8:9], v[16:17] op_sel_hi:[1,0]
	v_pk_mul_f32 v[6:7], v[6:7], v[16:17] op_sel_hi:[1,0]
	v_pk_mul_f32 v[4:5], v[4:5], v[16:17] op_sel_hi:[1,0]
	v_pk_mul_f32 v[18:19], v[2:3], v[16:17] op_sel_hi:[1,0]
	v_pk_mul_f32 v[2:3], v[0:1], v[16:17] op_sel_hi:[1,0]
	v_pk_mul_f32 v[156:157], v[12:13], s[100:101]
	v_pk_mul_f32 v[158:159], v[14:15], s[100:101]
	v_exp_f32_e32 v156, v156
	v_exp_f32_e32 v157, v157
	v_exp_f32_e32 v158, v158
	v_exp_f32_e32 v159, v159
	v_pk_add_f32 v[156:157], v[156:157], 1.0 op_sel_hi:[1,0]
	v_pk_add_f32 v[158:159], v[158:159], 1.0 op_sel_hi:[1,0]
	v_rcp_f32_e32 v156, v156
	v_rcp_f32_e32 v157, v157
	v_rcp_f32_e32 v158, v158
	v_rcp_f32_e32 v159, v159
	v_pk_mul_f32 v[156:157], v[12:13], v[156:157]
	v_pk_mul_f32 v[158:159], v[14:15], v[158:159]
	v_pk_mul_f32 v[156:157], v[4:5], v[156:157]
	v_pk_mul_f32 v[158:159], v[6:7], v[158:159]
	v_pk_mul_f32 v[160:161], v[8:9], s[100:101]
	v_pk_mul_f32 v[162:163], v[10:11], s[100:101]
	v_exp_f32_e32 v160, v160
	v_exp_f32_e32 v161, v161
	v_exp_f32_e32 v162, v162
	v_exp_f32_e32 v163, v163
	v_pk_add_f32 v[160:161], v[160:161], 1.0 op_sel_hi:[1,0]
	v_pk_add_f32 v[162:163], v[162:163], 1.0 op_sel_hi:[1,0]
	v_rcp_f32_e32 v160, v160
	v_rcp_f32_e32 v161, v161
	v_rcp_f32_e32 v162, v162
	v_rcp_f32_e32 v163, v163
	v_pk_mul_f32 v[160:161], v[8:9], v[160:161]
	v_pk_mul_f32 v[162:163], v[10:11], v[162:163]
	v_pk_mul_f32 v[160:161], v[2:3], v[160:161]
	v_pk_mul_f32 v[162:163], v[18:19], v[162:163]
	v_cvt_pk_bf16_f32 v0, v156, v157
	v_cvt_pk_bf16_f32 v1, v158, v159
	v_cvt_pk_bf16_f32 v2, v160, v161
	v_cvt_pk_bf16_f32 v3, v162, v163
	v_add_u32_e32 v4, 0xb0, v128
	v_mov_b32_e32 v5, v201
	v_lshlrev_b64 v[4:5], 7, v[4:5]
	v_lshl_add_u64 v[4:5], s[30:31], 0, v[4:5]
	v_lshl_add_u64 v[4:5], v[4:5], 0, s[16:17]
	v_lshl_add_u64 v[4:5], v[4:5], 0, v[200:201]
	global_store_dwordx4 v[4:5], v[0:3], off
	s_andn2_b64 vcc, exec, s[24:25]
	s_mov_b64 s[24:25], -1
	s_cbranch_vccnz .LBB0_1331
	s_andn2_b64 vcc, exec, s[0:1]
	s_cbranch_vccnz .LBB0_1330
	s_barrier
	s_branch .LBB0_1330
